# EpiIn: specialised fast path for rotary tiles with cos/sin loads 4 units ahead
# speedup vs baseline: 1.0114x; 1.0026x over previous
.LBB0_496:
	s_add_i32 s46, s46, s86
	v_or_b32_e32 v178, s46, v155
	v_ashrrev_i32_e32 v179, 31, v178
	s_add_i32 s6, s76, -12
	s_cmp_lt_u32 s6, 5
	s_cbranch_scc0 .Lin_generic
	s_cmpk_lt_i32 s77, 0x80
	s_cbranch_scc1 .Lin_rope
.Lin_generic:
	v_mov_b32_e32 v146, 1.0
	s_and_b64 vcc, exec, s[44:45]
	v_lshl_add_u64 v[180:181], v[178:179], 2, s[62:63]
	v_mov_b32_e32 v182, 1.0
	s_cbranch_vccnz .LBB0_498
	global_load_dword v0, v[180:181], off
	s_waitcnt vmcnt(0)
	v_fmamk_f32 v0, v0, 0x3a000000, v207
	v_mul_f32_e32 v147, 0x4b800000, v0
	v_cmp_gt_f32_e32 vcc, s33, v0
	s_nop 1
	v_cndmask_b32_e32 v0, v0, v147, vcc
	v_rsq_f32_e32 v0, v0
	s_nop 0
	v_mul_f32_e32 v147, 0x45800000, v0
	v_cndmask_b32_e32 v182, v0, v147, vcc

.Lin_rope:
	v_mad_i64_i32 v[246:247], s[42:43], v178, s79, 0
	v_lshl_add_u64 v[246:247], s[16:17], 0, v[246:247]
	v_lshl_add_u64 v[246:247], v[176:177], 1, v[246:247]
	v_lshl_add_u64 v[180:181], v[178:179], 2, s[62:63]
	s_bfe_u32 s6, s46, 0x80006
	v_mov_b32_e32 v251, 0
	v_mov_b32_e32 v183, 0
	s_and_b64 vcc, exec, s[44:45]
	s_cbranch_vccnz .Lin_rope_nossq
	global_load_dword v190, v[180:181], off
	global_load_dword v191, v[180:181], off offset:64
	global_load_dword v192, v[180:181], off offset:128
	global_load_dword v193, v[180:181], off offset:192
	global_load_dword v194, v[180:181], off offset:512
	global_load_dword v195, v[180:181], off offset:576
	global_load_dword v196, v[180:181], off offset:640
	global_load_dword v197, v[180:181], off offset:704
	v_mov_b32_e32 v0, s6
	v_cndmask_b32_e64 v250, v155, v0, s[36:37]
	v_lshlrev_b32_e32 v250, 7, v250
	v_lshl_add_u64 v[248:249], v[166:167], 0, v[250:251]
	global_load_dwordx4 v[198:201], v[248:249], off
	v_lshl_add_u64 v[248:249], v[164:165], 0, v[250:251]
	global_load_dwordx4 v[202:205], v[248:249], off
	v_lshl_add_u64 v[248:249], v[168:169], 0, v[250:251]
	global_load_dwordx4 v[230:233], v[248:249], off
	v_lshl_add_u64 v[248:249], v[170:171], 0, v[250:251]
	global_load_dwordx4 v[234:237], v[248:249], off
	v_mov_b32_e32 v0, s6
	v_cndmask_b32_e64 v250, v225, v0, s[36:37]
	v_lshlrev_b32_e32 v250, 7, v250
	v_lshl_add_u64 v[248:249], v[166:167], 0, v[250:251]
	global_load_dwordx4 v[238:241], v[248:249], off
	v_lshl_add_u64 v[248:249], v[164:165], 0, v[250:251]
	global_load_dwordx4 v[242:245], v[248:249], off
	v_lshl_add_u64 v[248:249], v[168:169], 0, v[250:251]
	global_load_dwordx4 v[146:149], v[248:249], off
	v_lshl_add_u64 v[248:249], v[170:171], 0, v[250:251]
	global_load_dwordx4 v[150:153], v[248:249], off
	s_waitcnt vmcnt(6)
	v_fmamk_f32 v182, v190, 0x3a000000, v207
	v_rsq_f32_e32 v182, v182
	s_nop 0
	v_pk_fma_f32 v[126:127], v[126:127], v[182:183], v[138:139] op_sel_hi:[1,0,1]
	v_pk_fma_f32 v[128:129], v[128:129], v[182:183], v[140:141] op_sel_hi:[1,0,1]
	v_pk_fma_f32 v[122:123], v[122:123], v[182:183], v[142:143] op_sel_hi:[1,0,1]
	v_pk_fma_f32 v[124:125], v[124:125], v[182:183], v[144:145] op_sel_hi:[1,0,1]
	v_pk_mul_f32 v[186:187], v[122:123], v[202:203]
	v_pk_mul_f32 v[188:189], v[124:125], v[204:205]
	v_pk_fma_f32 v[186:187], v[126:127], v[198:199], v[186:187] neg_lo:[0,0,1] neg_hi:[0,0,1]
	v_pk_fma_f32 v[188:189], v[128:129], v[200:201], v[188:189] neg_lo:[0,0,1] neg_hi:[0,0,1]
	v_pk_mul_f32 v[198:199], v[122:123], v[198:199]
	v_pk_mul_f32 v[200:201], v[124:125], v[200:201]
	v_pk_fma_f32 v[198:199], v[126:127], v[202:203], v[198:199]
	v_pk_fma_f32 v[200:201], v[128:129], v[204:205], v[200:201]
	v_cvt_pk_bf16_f32 v202, v186, v187
	v_cvt_pk_bf16_f32 v203, v188, v189
	v_cvt_pk_bf16_f32 v204, v198, v199
	v_cvt_pk_bf16_f32 v205, v200, v201
	v_lshl_add_u64 v[184:185], v[246:247], 0, 0
	global_store_dwordx4 v[184:185], v[202:205], off
	v_mov_b32_e32 v0, s6
	v_cndmask_b32_e64 v250, v226, v0, s[36:37]
	v_lshlrev_b32_e32 v250, 7, v250
	v_lshl_add_u64 v[248:249], v[166:167], 0, v[250:251]
	global_load_dwordx4 v[122:125], v[248:249], off
	v_lshl_add_u64 v[248:249], v[164:165], 0, v[250:251]
	global_load_dwordx4 v[126:129], v[248:249], off
	s_waitcnt vmcnt(7)
	v_pk_fma_f32 v[118:119], v[118:119], v[182:183], v[134:135] op_sel_hi:[1,0,1]
	v_pk_fma_f32 v[120:121], v[120:121], v[182:183], v[136:137] op_sel_hi:[1,0,1]
	v_pk_fma_f32 v[114:115], v[114:115], v[182:183], v[130:131] op_sel_hi:[1,0,1]
	v_pk_fma_f32 v[116:117], v[116:117], v[182:183], v[132:133] op_sel_hi:[1,0,1]
	v_pk_mul_f32 v[186:187], v[114:115], v[234:235]
	v_pk_mul_f32 v[188:189], v[116:117], v[236:237]
	v_pk_fma_f32 v[186:187], v[118:119], v[230:231], v[186:187] neg_lo:[0,0,1] neg_hi:[0,0,1]
	v_pk_fma_f32 v[188:189], v[120:121], v[232:233], v[188:189] neg_lo:[0,0,1] neg_hi:[0,0,1]
	v_pk_mul_f32 v[230:231], v[114:115], v[230:231]
	v_pk_mul_f32 v[232:233], v[116:117], v[232:233]
	v_pk_fma_f32 v[230:231], v[118:119], v[234:235], v[230:231]
	v_pk_fma_f32 v[232:233], v[120:121], v[236:237], v[232:233]
	v_cvt_pk_bf16_f32 v234, v186, v187
	v_cvt_pk_bf16_f32 v235, v188, v189
	v_cvt_pk_bf16_f32 v236, v230, v231
	v_cvt_pk_bf16_f32 v237, v232, v233
	global_store_dwordx4 v[184:185], v[234:237], off offset:64
	v_lshl_add_u64 v[248:249], v[168:169], 0, v[250:251]
	global_load_dwordx4 v[114:117], v[248:249], off
	v_lshl_add_u64 v[248:249], v[170:171], 0, v[250:251]
	global_load_dwordx4 v[118:121], v[248:249], off
	s_waitcnt vmcnt(8)
	v_fmamk_f32 v182, v191, 0x3a000000, v207
	v_rsq_f32_e32 v182, v182
	s_nop 0
	v_pk_fma_f32 v[110:111], v[110:111], v[182:183], v[138:139] op_sel_hi:[1,0,1]
	v_pk_fma_f32 v[112:113], v[112:113], v[182:183], v[140:141] op_sel_hi:[1,0,1]
	v_pk_fma_f32 v[106:107], v[106:107], v[182:183], v[142:143] op_sel_hi:[1,0,1]
	v_pk_fma_f32 v[108:109], v[108:109], v[182:183], v[144:145] op_sel_hi:[1,0,1]
	v_pk_mul_f32 v[186:187], v[106:107], v[242:243]
	v_pk_mul_f32 v[188:189], v[108:109], v[244:245]
	v_pk_fma_f32 v[186:187], v[110:111], v[238:239], v[186:187] neg_lo:[0,0,1] neg_hi:[0,0,1]
	v_pk_fma_f32 v[188:189], v[112:113], v[240:241], v[188:189] neg_lo:[0,0,1] neg_hi:[0,0,1]
	v_pk_mul_f32 v[238:239], v[106:107], v[238:239]
	v_pk_mul_f32 v[240:241], v[108:109], v[240:241]
	v_pk_fma_f32 v[238:239], v[110:111], v[242:243], v[238:239]
	v_pk_fma_f32 v[240:241], v[112:113], v[244:245], v[240:241]
	v_cvt_pk_bf16_f32 v242, v186, v187
	v_cvt_pk_bf16_f32 v243, v188, v189
	v_cvt_pk_bf16_f32 v244, v238, v239
	v_cvt_pk_bf16_f32 v245, v240, v241
	s_mov_b64 s[42:43], 0x24400
	v_lshl_add_u64 v[184:185], v[246:247], 0, s[42:43]
	global_store_dwordx4 v[184:185], v[242:245], off
	v_mov_b32_e32 v0, s6
	v_cndmask_b32_e64 v250, v227, v0, s[36:37]
	v_lshlrev_b32_e32 v250, 7, v250
	v_lshl_add_u64 v[248:249], v[166:167], 0, v[250:251]
	global_load_dwordx4 v[106:109], v[248:249], off
	v_lshl_add_u64 v[248:249], v[164:165], 0, v[250:251]
	global_load_dwordx4 v[110:113], v[248:249], off
	s_waitcnt vmcnt(9)
	v_pk_fma_f32 v[102:103], v[102:103], v[182:183], v[134:135] op_sel_hi:[1,0,1]
	v_pk_fma_f32 v[104:105], v[104:105], v[182:183], v[136:137] op_sel_hi:[1,0,1]
	v_pk_fma_f32 v[98:99], v[98:99], v[182:183], v[130:131] op_sel_hi:[1,0,1]
	v_pk_fma_f32 v[100:101], v[100:101], v[182:183], v[132:133] op_sel_hi:[1,0,1]
	v_pk_mul_f32 v[186:187], v[98:99], v[150:151]
	v_pk_mul_f32 v[188:189], v[100:101], v[152:153]
	v_pk_fma_f32 v[186:187], v[102:103], v[146:147], v[186:187] neg_lo:[0,0,1] neg_hi:[0,0,1]
	v_pk_fma_f32 v[188:189], v[104:105], v[148:149], v[188:189] neg_lo:[0,0,1] neg_hi:[0,0,1]
	v_pk_mul_f32 v[146:147], v[98:99], v[146:147]
	v_pk_mul_f32 v[148:149], v[100:101], v[148:149]
	v_pk_fma_f32 v[146:147], v[102:103], v[150:151], v[146:147]
	v_pk_fma_f32 v[148:149], v[104:105], v[152:153], v[148:149]
	v_cvt_pk_bf16_f32 v150, v186, v187
	v_cvt_pk_bf16_f32 v151, v188, v189
	v_cvt_pk_bf16_f32 v152, v146, v147
	v_cvt_pk_bf16_f32 v153, v148, v149
	global_store_dwordx4 v[184:185], v[150:153], off offset:64
	v_lshl_add_u64 v[248:249], v[168:169], 0, v[250:251]
	global_load_dwordx4 v[98:101], v[248:249], off
	v_lshl_add_u64 v[248:249], v[170:171], 0, v[250:251]
	global_load_dwordx4 v[102:105], v[248:249], off
	s_waitcnt vmcnt(9)
	v_fmamk_f32 v182, v192, 0x3a000000, v207
	v_rsq_f32_e32 v182, v182
	s_nop 0
	v_pk_fma_f32 v[94:95], v[94:95], v[182:183], v[138:139] op_sel_hi:[1,0,1]
	v_pk_fma_f32 v[96:97], v[96:97], v[182:183], v[140:141] op_sel_hi:[1,0,1]
	v_pk_fma_f32 v[90:91], v[90:91], v[182:183], v[142:143] op_sel_hi:[1,0,1]
	v_pk_fma_f32 v[92:93], v[92:93], v[182:183], v[144:145] op_sel_hi:[1,0,1]
	v_pk_mul_f32 v[186:187], v[90:91], v[126:127]
	v_pk_mul_f32 v[188:189], v[92:93], v[128:129]
	v_pk_fma_f32 v[186:187], v[94:95], v[122:123], v[186:187] neg_lo:[0,0,1] neg_hi:[0,0,1]
	v_pk_fma_f32 v[188:189], v[96:97], v[124:125], v[188:189] neg_lo:[0,0,1] neg_hi:[0,0,1]
	v_pk_mul_f32 v[122:123], v[90:91], v[122:123]
	v_pk_mul_f32 v[124:125], v[92:93], v[124:125]
	v_pk_fma_f32 v[122:123], v[94:95], v[126:127], v[122:123]
	v_pk_fma_f32 v[124:125], v[96:97], v[128:129], v[124:125]
	v_cvt_pk_bf16_f32 v126, v186, v187
	v_cvt_pk_bf16_f32 v127, v188, v189
	v_cvt_pk_bf16_f32 v128, v122, v123
	v_cvt_pk_bf16_f32 v129, v124, v125
	s_mov_b64 s[42:43], 0x48800
	v_lshl_add_u64 v[184:185], v[246:247], 0, s[42:43]
	global_store_dwordx4 v[184:185], v[126:129], off
	s_add_i32 s6, s6, 2
	v_mov_b32_e32 v0, s6
	v_cndmask_b32_e64 v250, v155, v0, s[36:37]
	v_lshlrev_b32_e32 v250, 7, v250
	v_lshl_add_u64 v[248:249], v[166:167], 0, v[250:251]
	global_load_dwordx4 v[90:93], v[248:249], off
	v_lshl_add_u64 v[248:249], v[164:165], 0, v[250:251]
	global_load_dwordx4 v[94:97], v[248:249], off
	s_waitcnt vmcnt(9)
	v_pk_fma_f32 v[86:87], v[86:87], v[182:183], v[134:135] op_sel_hi:[1,0,1]
	v_pk_fma_f32 v[88:89], v[88:89], v[182:183], v[136:137] op_sel_hi:[1,0,1]
	v_pk_fma_f32 v[82:83], v[82:83], v[182:183], v[130:131] op_sel_hi:[1,0,1]
	v_pk_fma_f32 v[84:85], v[84:85], v[182:183], v[132:133] op_sel_hi:[1,0,1]
	v_pk_mul_f32 v[186:187], v[82:83], v[118:119]
	v_pk_mul_f32 v[188:189], v[84:85], v[120:121]
	v_pk_fma_f32 v[186:187], v[86:87], v[114:115], v[186:187] neg_lo:[0,0,1] neg_hi:[0,0,1]
	v_pk_fma_f32 v[188:189], v[88:89], v[116:117], v[188:189] neg_lo:[0,0,1] neg_hi:[0,0,1]
	v_pk_mul_f32 v[114:115], v[82:83], v[114:115]
	v_pk_mul_f32 v[116:117], v[84:85], v[116:117]
	v_pk_fma_f32 v[114:115], v[86:87], v[118:119], v[114:115]
	v_pk_fma_f32 v[116:117], v[88:89], v[120:121], v[116:117]
	v_cvt_pk_bf16_f32 v118, v186, v187
	v_cvt_pk_bf16_f32 v119, v188, v189
	v_cvt_pk_bf16_f32 v120, v114, v115
	v_cvt_pk_bf16_f32 v121, v116, v117
	global_store_dwordx4 v[184:185], v[118:121], off offset:64
	v_lshl_add_u64 v[248:249], v[168:169], 0, v[250:251]
	global_load_dwordx4 v[82:85], v[248:249], off
	v_lshl_add_u64 v[248:249], v[170:171], 0, v[250:251]
	global_load_dwordx4 v[86:89], v[248:249], off
	s_waitcnt vmcnt(9)
	v_fmamk_f32 v182, v193, 0x3a000000, v207
	v_rsq_f32_e32 v182, v182
	s_nop 0
	v_pk_fma_f32 v[78:79], v[78:79], v[182:183], v[138:139] op_sel_hi:[1,0,1]
	v_pk_fma_f32 v[80:81], v[80:81], v[182:183], v[140:141] op_sel_hi:[1,0,1]
	v_pk_fma_f32 v[74:75], v[74:75], v[182:183], v[142:143] op_sel_hi:[1,0,1]
	v_pk_fma_f32 v[76:77], v[76:77], v[182:183], v[144:145] op_sel_hi:[1,0,1]
	v_pk_mul_f32 v[186:187], v[74:75], v[110:111]
	v_pk_mul_f32 v[188:189], v[76:77], v[112:113]
	v_pk_fma_f32 v[186:187], v[78:79], v[106:107], v[186:187] neg_lo:[0,0,1] neg_hi:[0,0,1]
	v_pk_fma_f32 v[188:189], v[80:81], v[108:109], v[188:189] neg_lo:[0,0,1] neg_hi:[0,0,1]
	v_pk_mul_f32 v[106:107], v[74:75], v[106:107]
	v_pk_mul_f32 v[108:109], v[76:77], v[108:109]
	v_pk_fma_f32 v[106:107], v[78:79], v[110:111], v[106:107]
	v_pk_fma_f32 v[108:109], v[80:81], v[112:113], v[108:109]
	v_cvt_pk_bf16_f32 v110, v186, v187
	v_cvt_pk_bf16_f32 v111, v188, v189
	v_cvt_pk_bf16_f32 v112, v106, v107
	v_cvt_pk_bf16_f32 v113, v108, v109
	s_mov_b64 s[42:43], 0x6cc00
	v_lshl_add_u64 v[184:185], v[246:247], 0, s[42:43]
	global_store_dwordx4 v[184:185], v[110:113], off
	v_mov_b32_e32 v0, s6
	v_cndmask_b32_e64 v250, v225, v0, s[36:37]
	v_lshlrev_b32_e32 v250, 7, v250
	v_lshl_add_u64 v[248:249], v[166:167], 0, v[250:251]
	global_load_dwordx4 v[74:77], v[248:249], off
	v_lshl_add_u64 v[248:249], v[164:165], 0, v[250:251]
	global_load_dwordx4 v[78:81], v[248:249], off
	s_waitcnt vmcnt(9)
	v_pk_fma_f32 v[70:71], v[70:71], v[182:183], v[134:135] op_sel_hi:[1,0,1]
	v_pk_fma_f32 v[72:73], v[72:73], v[182:183], v[136:137] op_sel_hi:[1,0,1]
	v_pk_fma_f32 v[66:67], v[66:67], v[182:183], v[130:131] op_sel_hi:[1,0,1]
	v_pk_fma_f32 v[68:69], v[68:69], v[182:183], v[132:133] op_sel_hi:[1,0,1]
	v_pk_mul_f32 v[186:187], v[66:67], v[102:103]
	v_pk_mul_f32 v[188:189], v[68:69], v[104:105]
	v_pk_fma_f32 v[186:187], v[70:71], v[98:99], v[186:187] neg_lo:[0,0,1] neg_hi:[0,0,1]
	v_pk_fma_f32 v[188:189], v[72:73], v[100:101], v[188:189] neg_lo:[0,0,1] neg_hi:[0,0,1]
	v_pk_mul_f32 v[98:99], v[66:67], v[98:99]
	v_pk_mul_f32 v[100:101], v[68:69], v[100:101]
	v_pk_fma_f32 v[98:99], v[70:71], v[102:103], v[98:99]
	v_pk_fma_f32 v[100:101], v[72:73], v[104:105], v[100:101]
	v_cvt_pk_bf16_f32 v102, v186, v187
	v_cvt_pk_bf16_f32 v103, v188, v189
	v_cvt_pk_bf16_f32 v104, v98, v99
	v_cvt_pk_bf16_f32 v105, v100, v101
	global_store_dwordx4 v[184:185], v[102:105], off offset:64
	v_lshl_add_u64 v[248:249], v[168:169], 0, v[250:251]
	global_load_dwordx4 v[66:69], v[248:249], off
	v_lshl_add_u64 v[248:249], v[170:171], 0, v[250:251]
	global_load_dwordx4 v[70:73], v[248:249], off
	s_waitcnt vmcnt(9)
	v_fmamk_f32 v182, v194, 0x3a000000, v207
	v_rsq_f32_e32 v182, v182
	s_nop 0
	v_pk_fma_f32 v[62:63], v[62:63], v[182:183], v[138:139] op_sel_hi:[1,0,1]
	v_pk_fma_f32 v[64:65], v[64:65], v[182:183], v[140:141] op_sel_hi:[1,0,1]
	v_pk_fma_f32 v[58:59], v[58:59], v[182:183], v[142:143] op_sel_hi:[1,0,1]
	v_pk_fma_f32 v[60:61], v[60:61], v[182:183], v[144:145] op_sel_hi:[1,0,1]
	v_pk_mul_f32 v[186:187], v[58:59], v[94:95]
	v_pk_mul_f32 v[188:189], v[60:61], v[96:97]
	v_pk_fma_f32 v[186:187], v[62:63], v[90:91], v[186:187] neg_lo:[0,0,1] neg_hi:[0,0,1]
	v_pk_fma_f32 v[188:189], v[64:65], v[92:93], v[188:189] neg_lo:[0,0,1] neg_hi:[0,0,1]
	v_pk_mul_f32 v[90:91], v[58:59], v[90:91]
	v_pk_mul_f32 v[92:93], v[60:61], v[92:93]
	v_pk_fma_f32 v[90:91], v[62:63], v[94:95], v[90:91]
	v_pk_fma_f32 v[92:93], v[64:65], v[96:97], v[92:93]
	v_cvt_pk_bf16_f32 v94, v186, v187
	v_cvt_pk_bf16_f32 v95, v188, v189
	v_cvt_pk_bf16_f32 v96, v90, v91
	v_cvt_pk_bf16_f32 v97, v92, v93
	s_mov_b64 s[42:43], 0x122000
	v_lshl_add_u64 v[184:185], v[246:247], 0, s[42:43]
	global_store_dwordx4 v[184:185], v[94:97], off
	v_mov_b32_e32 v0, s6
	v_cndmask_b32_e64 v250, v226, v0, s[36:37]
	v_lshlrev_b32_e32 v250, 7, v250
	v_lshl_add_u64 v[248:249], v[166:167], 0, v[250:251]
	global_load_dwordx4 v[58:61], v[248:249], off
	v_lshl_add_u64 v[248:249], v[164:165], 0, v[250:251]
	global_load_dwordx4 v[62:65], v[248:249], off
	s_waitcnt vmcnt(9)
	v_pk_fma_f32 v[54:55], v[54:55], v[182:183], v[134:135] op_sel_hi:[1,0,1]
	v_pk_fma_f32 v[56:57], v[56:57], v[182:183], v[136:137] op_sel_hi:[1,0,1]
	v_pk_fma_f32 v[50:51], v[50:51], v[182:183], v[130:131] op_sel_hi:[1,0,1]
	v_pk_fma_f32 v[52:53], v[52:53], v[182:183], v[132:133] op_sel_hi:[1,0,1]
	v_pk_mul_f32 v[186:187], v[50:51], v[86:87]
	v_pk_mul_f32 v[188:189], v[52:53], v[88:89]
	v_pk_fma_f32 v[186:187], v[54:55], v[82:83], v[186:187] neg_lo:[0,0,1] neg_hi:[0,0,1]
	v_pk_fma_f32 v[188:189], v[56:57], v[84:85], v[188:189] neg_lo:[0,0,1] neg_hi:[0,0,1]
	v_pk_mul_f32 v[82:83], v[50:51], v[82:83]
	v_pk_mul_f32 v[84:85], v[52:53], v[84:85]
	v_pk_fma_f32 v[82:83], v[54:55], v[86:87], v[82:83]
	v_pk_fma_f32 v[84:85], v[56:57], v[88:89], v[84:85]
	v_cvt_pk_bf16_f32 v86, v186, v187
	v_cvt_pk_bf16_f32 v87, v188, v189
	v_cvt_pk_bf16_f32 v88, v82, v83
	v_cvt_pk_bf16_f32 v89, v84, v85
	global_store_dwordx4 v[184:185], v[86:89], off offset:64
	v_lshl_add_u64 v[248:249], v[168:169], 0, v[250:251]
	global_load_dwordx4 v[50:53], v[248:249], off
	v_lshl_add_u64 v[248:249], v[170:171], 0, v[250:251]
	global_load_dwordx4 v[54:57], v[248:249], off
	s_waitcnt vmcnt(9)
	v_fmamk_f32 v182, v195, 0x3a000000, v207
	v_rsq_f32_e32 v182, v182
	s_nop 0
	v_pk_fma_f32 v[46:47], v[46:47], v[182:183], v[138:139] op_sel_hi:[1,0,1]
	v_pk_fma_f32 v[48:49], v[48:49], v[182:183], v[140:141] op_sel_hi:[1,0,1]
	v_pk_fma_f32 v[42:43], v[42:43], v[182:183], v[142:143] op_sel_hi:[1,0,1]
	v_pk_fma_f32 v[44:45], v[44:45], v[182:183], v[144:145] op_sel_hi:[1,0,1]
	v_pk_mul_f32 v[186:187], v[42:43], v[78:79]
	v_pk_mul_f32 v[188:189], v[44:45], v[80:81]
	v_pk_fma_f32 v[186:187], v[46:47], v[74:75], v[186:187] neg_lo:[0,0,1] neg_hi:[0,0,1]
	v_pk_fma_f32 v[188:189], v[48:49], v[76:77], v[188:189] neg_lo:[0,0,1] neg_hi:[0,0,1]
	v_pk_mul_f32 v[74:75], v[42:43], v[74:75]
	v_pk_mul_f32 v[76:77], v[44:45], v[76:77]
	v_pk_fma_f32 v[74:75], v[46:47], v[78:79], v[74:75]
	v_pk_fma_f32 v[76:77], v[48:49], v[80:81], v[76:77]
	v_cvt_pk_bf16_f32 v78, v186, v187
	v_cvt_pk_bf16_f32 v79, v188, v189
	v_cvt_pk_bf16_f32 v80, v74, v75
	v_cvt_pk_bf16_f32 v81, v76, v77
	s_mov_b64 s[42:43], 0x146400
	v_lshl_add_u64 v[184:185], v[246:247], 0, s[42:43]
	global_store_dwordx4 v[184:185], v[78:81], off
	v_mov_b32_e32 v0, s6
	v_cndmask_b32_e64 v250, v227, v0, s[36:37]
	v_lshlrev_b32_e32 v250, 7, v250
	v_lshl_add_u64 v[248:249], v[166:167], 0, v[250:251]
	global_load_dwordx4 v[42:45], v[248:249], off
	v_lshl_add_u64 v[248:249], v[164:165], 0, v[250:251]
	global_load_dwordx4 v[46:49], v[248:249], off
	s_waitcnt vmcnt(9)
	v_pk_fma_f32 v[38:39], v[38:39], v[182:183], v[134:135] op_sel_hi:[1,0,1]
	v_pk_fma_f32 v[40:41], v[40:41], v[182:183], v[136:137] op_sel_hi:[1,0,1]
	v_pk_fma_f32 v[34:35], v[34:35], v[182:183], v[130:131] op_sel_hi:[1,0,1]
	v_pk_fma_f32 v[36:37], v[36:37], v[182:183], v[132:133] op_sel_hi:[1,0,1]
	v_pk_mul_f32 v[186:187], v[34:35], v[70:71]
	v_pk_mul_f32 v[188:189], v[36:37], v[72:73]
	v_pk_fma_f32 v[186:187], v[38:39], v[66:67], v[186:187] neg_lo:[0,0,1] neg_hi:[0,0,1]
	v_pk_fma_f32 v[188:189], v[40:41], v[68:69], v[188:189] neg_lo:[0,0,1] neg_hi:[0,0,1]
	v_pk_mul_f32 v[66:67], v[34:35], v[66:67]
	v_pk_mul_f32 v[68:69], v[36:37], v[68:69]
	v_pk_fma_f32 v[66:67], v[38:39], v[70:71], v[66:67]
	v_pk_fma_f32 v[68:69], v[40:41], v[72:73], v[68:69]
	v_cvt_pk_bf16_f32 v70, v186, v187
	v_cvt_pk_bf16_f32 v71, v188, v189
	v_cvt_pk_bf16_f32 v72, v66, v67
	v_cvt_pk_bf16_f32 v73, v68, v69
	global_store_dwordx4 v[184:185], v[70:73], off offset:64
	v_lshl_add_u64 v[248:249], v[168:169], 0, v[250:251]
	global_load_dwordx4 v[34:37], v[248:249], off
	v_lshl_add_u64 v[248:249], v[170:171], 0, v[250:251]
	global_load_dwordx4 v[38:41], v[248:249], off
	s_waitcnt vmcnt(9)
	v_fmamk_f32 v182, v196, 0x3a000000, v207
	v_rsq_f32_e32 v182, v182
	s_nop 0
	v_pk_fma_f32 v[30:31], v[30:31], v[182:183], v[138:139] op_sel_hi:[1,0,1]
	v_pk_fma_f32 v[32:33], v[32:33], v[182:183], v[140:141] op_sel_hi:[1,0,1]
	v_pk_fma_f32 v[26:27], v[26:27], v[182:183], v[142:143] op_sel_hi:[1,0,1]
	v_pk_fma_f32 v[28:29], v[28:29], v[182:183], v[144:145] op_sel_hi:[1,0,1]
	v_pk_mul_f32 v[186:187], v[26:27], v[62:63]
	v_pk_mul_f32 v[188:189], v[28:29], v[64:65]
	v_pk_fma_f32 v[186:187], v[30:31], v[58:59], v[186:187] neg_lo:[0,0,1] neg_hi:[0,0,1]
	v_pk_fma_f32 v[188:189], v[32:33], v[60:61], v[188:189] neg_lo:[0,0,1] neg_hi:[0,0,1]
	v_pk_mul_f32 v[58:59], v[26:27], v[58:59]
	v_pk_mul_f32 v[60:61], v[28:29], v[60:61]
	v_pk_fma_f32 v[58:59], v[30:31], v[62:63], v[58:59]
	v_pk_fma_f32 v[60:61], v[32:33], v[64:65], v[60:61]
	v_cvt_pk_bf16_f32 v62, v186, v187
	v_cvt_pk_bf16_f32 v63, v188, v189
	v_cvt_pk_bf16_f32 v64, v58, v59
	v_cvt_pk_bf16_f32 v65, v60, v61
	s_mov_b64 s[42:43], 0x16a800
	v_lshl_add_u64 v[184:185], v[246:247], 0, s[42:43]
	global_store_dwordx4 v[184:185], v[62:65], off
	s_waitcnt vmcnt(7)
	v_pk_fma_f32 v[22:23], v[22:23], v[182:183], v[134:135] op_sel_hi:[1,0,1]
	v_pk_fma_f32 v[24:25], v[24:25], v[182:183], v[136:137] op_sel_hi:[1,0,1]
	v_pk_fma_f32 v[18:19], v[18:19], v[182:183], v[130:131] op_sel_hi:[1,0,1]
	v_pk_fma_f32 v[20:21], v[20:21], v[182:183], v[132:133] op_sel_hi:[1,0,1]
	v_pk_mul_f32 v[186:187], v[18:19], v[54:55]
	v_pk_mul_f32 v[188:189], v[20:21], v[56:57]
	v_pk_fma_f32 v[186:187], v[22:23], v[50:51], v[186:187] neg_lo:[0,0,1] neg_hi:[0,0,1]
	v_pk_fma_f32 v[188:189], v[24:25], v[52:53], v[188:189] neg_lo:[0,0,1] neg_hi:[0,0,1]
	v_pk_mul_f32 v[50:51], v[18:19], v[50:51]
	v_pk_mul_f32 v[52:53], v[20:21], v[52:53]
	v_pk_fma_f32 v[50:51], v[22:23], v[54:55], v[50:51]
	v_pk_fma_f32 v[52:53], v[24:25], v[56:57], v[52:53]
	v_cvt_pk_bf16_f32 v54, v186, v187
	v_cvt_pk_bf16_f32 v55, v188, v189
	v_cvt_pk_bf16_f32 v56, v50, v51
	v_cvt_pk_bf16_f32 v57, v52, v53
	global_store_dwordx4 v[184:185], v[54:57], off offset:64
	s_waitcnt vmcnt(5)
	v_fmamk_f32 v182, v197, 0x3a000000, v207
	v_rsq_f32_e32 v182, v182
	s_nop 0
	v_pk_fma_f32 v[14:15], v[14:15], v[182:183], v[138:139] op_sel_hi:[1,0,1]
	v_pk_fma_f32 v[16:17], v[16:17], v[182:183], v[140:141] op_sel_hi:[1,0,1]
	v_pk_fma_f32 v[10:11], v[10:11], v[182:183], v[142:143] op_sel_hi:[1,0,1]
	v_pk_fma_f32 v[12:13], v[12:13], v[182:183], v[144:145] op_sel_hi:[1,0,1]
	v_pk_mul_f32 v[186:187], v[10:11], v[46:47]
	v_pk_mul_f32 v[188:189], v[12:13], v[48:49]
	v_pk_fma_f32 v[186:187], v[14:15], v[42:43], v[186:187] neg_lo:[0,0,1] neg_hi:[0,0,1]
	v_pk_fma_f32 v[188:189], v[16:17], v[44:45], v[188:189] neg_lo:[0,0,1] neg_hi:[0,0,1]
	v_pk_mul_f32 v[42:43], v[10:11], v[42:43]
	v_pk_mul_f32 v[44:45], v[12:13], v[44:45]
	v_pk_fma_f32 v[42:43], v[14:15], v[46:47], v[42:43]
	v_pk_fma_f32 v[44:45], v[16:17], v[48:49], v[44:45]
	v_cvt_pk_bf16_f32 v46, v186, v187
	v_cvt_pk_bf16_f32 v47, v188, v189
	v_cvt_pk_bf16_f32 v48, v42, v43
	v_cvt_pk_bf16_f32 v49, v44, v45
	s_mov_b64 s[42:43], 0x18ec00
	v_lshl_add_u64 v[184:185], v[246:247], 0, s[42:43]
	global_store_dwordx4 v[184:185], v[46:49], off
	s_waitcnt vmcnt(3)
	v_pk_fma_f32 v[6:7], v[6:7], v[182:183], v[134:135] op_sel_hi:[1,0,1]
	v_pk_fma_f32 v[8:9], v[8:9], v[182:183], v[136:137] op_sel_hi:[1,0,1]
	v_pk_fma_f32 v[2:3], v[2:3], v[182:183], v[130:131] op_sel_hi:[1,0,1]
	v_pk_fma_f32 v[4:5], v[4:5], v[182:183], v[132:133] op_sel_hi:[1,0,1]
	v_pk_mul_f32 v[186:187], v[2:3], v[38:39]
	v_pk_mul_f32 v[188:189], v[4:5], v[40:41]
	v_pk_fma_f32 v[186:187], v[6:7], v[34:35], v[186:187] neg_lo:[0,0,1] neg_hi:[0,0,1]
	v_pk_fma_f32 v[188:189], v[8:9], v[36:37], v[188:189] neg_lo:[0,0,1] neg_hi:[0,0,1]
	v_pk_mul_f32 v[34:35], v[2:3], v[34:35]
	v_pk_mul_f32 v[36:37], v[4:5], v[36:37]
	v_pk_fma_f32 v[34:35], v[6:7], v[38:39], v[34:35]
	v_pk_fma_f32 v[36:37], v[8:9], v[40:41], v[36:37]
	v_cvt_pk_bf16_f32 v38, v186, v187
	v_cvt_pk_bf16_f32 v39, v188, v189
	v_cvt_pk_bf16_f32 v40, v34, v35
	v_cvt_pk_bf16_f32 v41, v36, v37
	global_store_dwordx4 v[184:185], v[38:41], off offset:64
	s_branch .LBB0_375
.Lin_rope_nossq:
	v_mov_b32_e32 v0, s6
	v_cndmask_b32_e64 v250, v155, v0, s[36:37]
	v_lshlrev_b32_e32 v250, 7, v250
	v_lshl_add_u64 v[248:249], v[166:167], 0, v[250:251]
	global_load_dwordx4 v[198:201], v[248:249], off
	v_lshl_add_u64 v[248:249], v[164:165], 0, v[250:251]
	global_load_dwordx4 v[202:205], v[248:249], off
	v_lshl_add_u64 v[248:249], v[168:169], 0, v[250:251]
	global_load_dwordx4 v[230:233], v[248:249], off
	v_lshl_add_u64 v[248:249], v[170:171], 0, v[250:251]
	global_load_dwordx4 v[234:237], v[248:249], off
	v_mov_b32_e32 v0, s6
	v_cndmask_b32_e64 v250, v225, v0, s[36:37]
	v_lshlrev_b32_e32 v250, 7, v250
	v_lshl_add_u64 v[248:249], v[166:167], 0, v[250:251]
	global_load_dwordx4 v[238:241], v[248:249], off
	v_lshl_add_u64 v[248:249], v[164:165], 0, v[250:251]
	global_load_dwordx4 v[242:245], v[248:249], off
	v_lshl_add_u64 v[248:249], v[168:169], 0, v[250:251]
	global_load_dwordx4 v[146:149], v[248:249], off
	v_lshl_add_u64 v[248:249], v[170:171], 0, v[250:251]
	global_load_dwordx4 v[150:153], v[248:249], off
	s_waitcnt vmcnt(6)
	v_pk_mul_f32 v[186:187], v[122:123], v[202:203]
	v_pk_mul_f32 v[188:189], v[124:125], v[204:205]
	v_pk_fma_f32 v[186:187], v[126:127], v[198:199], v[186:187] neg_lo:[0,0,1] neg_hi:[0,0,1]
	v_pk_fma_f32 v[188:189], v[128:129], v[200:201], v[188:189] neg_lo:[0,0,1] neg_hi:[0,0,1]
	v_pk_mul_f32 v[198:199], v[122:123], v[198:199]
	v_pk_mul_f32 v[200:201], v[124:125], v[200:201]
	v_pk_fma_f32 v[198:199], v[126:127], v[202:203], v[198:199]
	v_pk_fma_f32 v[200:201], v[128:129], v[204:205], v[200:201]
	v_cvt_pk_bf16_f32 v202, v186, v187
	v_cvt_pk_bf16_f32 v203, v188, v189
	v_cvt_pk_bf16_f32 v204, v198, v199
	v_cvt_pk_bf16_f32 v205, v200, v201
	v_lshl_add_u64 v[184:185], v[246:247], 0, 0
	global_store_dwordx4 v[184:185], v[202:205], off
	v_mov_b32_e32 v0, s6
	v_cndmask_b32_e64 v250, v226, v0, s[36:37]
	v_lshlrev_b32_e32 v250, 7, v250
	v_lshl_add_u64 v[248:249], v[166:167], 0, v[250:251]
	global_load_dwordx4 v[122:125], v[248:249], off
	v_lshl_add_u64 v[248:249], v[164:165], 0, v[250:251]
	global_load_dwordx4 v[126:129], v[248:249], off
	s_waitcnt vmcnt(7)
	v_pk_mul_f32 v[186:187], v[114:115], v[234:235]
	v_pk_mul_f32 v[188:189], v[116:117], v[236:237]
	v_pk_fma_f32 v[186:187], v[118:119], v[230:231], v[186:187] neg_lo:[0,0,1] neg_hi:[0,0,1]
	v_pk_fma_f32 v[188:189], v[120:121], v[232:233], v[188:189] neg_lo:[0,0,1] neg_hi:[0,0,1]
	v_pk_mul_f32 v[230:231], v[114:115], v[230:231]
	v_pk_mul_f32 v[232:233], v[116:117], v[232:233]
	v_pk_fma_f32 v[230:231], v[118:119], v[234:235], v[230:231]
	v_pk_fma_f32 v[232:233], v[120:121], v[236:237], v[232:233]
	v_cvt_pk_bf16_f32 v234, v186, v187
	v_cvt_pk_bf16_f32 v235, v188, v189
	v_cvt_pk_bf16_f32 v236, v230, v231
	v_cvt_pk_bf16_f32 v237, v232, v233
	global_store_dwordx4 v[184:185], v[234:237], off offset:64
	v_lshl_add_u64 v[248:249], v[168:169], 0, v[250:251]
	global_load_dwordx4 v[114:117], v[248:249], off
	v_lshl_add_u64 v[248:249], v[170:171], 0, v[250:251]
	global_load_dwordx4 v[118:121], v[248:249], off
	s_waitcnt vmcnt(8)
	v_pk_mul_f32 v[186:187], v[106:107], v[242:243]
	v_pk_mul_f32 v[188:189], v[108:109], v[244:245]
	v_pk_fma_f32 v[186:187], v[110:111], v[238:239], v[186:187] neg_lo:[0,0,1] neg_hi:[0,0,1]
	v_pk_fma_f32 v[188:189], v[112:113], v[240:241], v[188:189] neg_lo:[0,0,1] neg_hi:[0,0,1]
	v_pk_mul_f32 v[238:239], v[106:107], v[238:239]
	v_pk_mul_f32 v[240:241], v[108:109], v[240:241]
	v_pk_fma_f32 v[238:239], v[110:111], v[242:243], v[238:239]
	v_pk_fma_f32 v[240:241], v[112:113], v[244:245], v[240:241]
	v_cvt_pk_bf16_f32 v242, v186, v187
	v_cvt_pk_bf16_f32 v243, v188, v189
	v_cvt_pk_bf16_f32 v244, v238, v239
	v_cvt_pk_bf16_f32 v245, v240, v241
	s_mov_b64 s[42:43], 0x24400
	v_lshl_add_u64 v[184:185], v[246:247], 0, s[42:43]
	global_store_dwordx4 v[184:185], v[242:245], off
	v_mov_b32_e32 v0, s6
	v_cndmask_b32_e64 v250, v227, v0, s[36:37]
	v_lshlrev_b32_e32 v250, 7, v250
	v_lshl_add_u64 v[248:249], v[166:167], 0, v[250:251]
	global_load_dwordx4 v[106:109], v[248:249], off
	v_lshl_add_u64 v[248:249], v[164:165], 0, v[250:251]
	global_load_dwordx4 v[110:113], v[248:249], off
	s_waitcnt vmcnt(9)
	v_pk_mul_f32 v[186:187], v[98:99], v[150:151]
	v_pk_mul_f32 v[188:189], v[100:101], v[152:153]
	v_pk_fma_f32 v[186:187], v[102:103], v[146:147], v[186:187] neg_lo:[0,0,1] neg_hi:[0,0,1]
	v_pk_fma_f32 v[188:189], v[104:105], v[148:149], v[188:189] neg_lo:[0,0,1] neg_hi:[0,0,1]
	v_pk_mul_f32 v[146:147], v[98:99], v[146:147]
	v_pk_mul_f32 v[148:149], v[100:101], v[148:149]
	v_pk_fma_f32 v[146:147], v[102:103], v[150:151], v[146:147]
	v_pk_fma_f32 v[148:149], v[104:105], v[152:153], v[148:149]
	v_cvt_pk_bf16_f32 v150, v186, v187
	v_cvt_pk_bf16_f32 v151, v188, v189
	v_cvt_pk_bf16_f32 v152, v146, v147
	v_cvt_pk_bf16_f32 v153, v148, v149
	global_store_dwordx4 v[184:185], v[150:153], off offset:64
	v_lshl_add_u64 v[248:249], v[168:169], 0, v[250:251]
	global_load_dwordx4 v[98:101], v[248:249], off
	v_lshl_add_u64 v[248:249], v[170:171], 0, v[250:251]
	global_load_dwordx4 v[102:105], v[248:249], off
	s_waitcnt vmcnt(9)
	v_pk_mul_f32 v[186:187], v[90:91], v[126:127]
	v_pk_mul_f32 v[188:189], v[92:93], v[128:129]
	v_pk_fma_f32 v[186:187], v[94:95], v[122:123], v[186:187] neg_lo:[0,0,1] neg_hi:[0,0,1]
	v_pk_fma_f32 v[188:189], v[96:97], v[124:125], v[188:189] neg_lo:[0,0,1] neg_hi:[0,0,1]
	v_pk_mul_f32 v[122:123], v[90:91], v[122:123]
	v_pk_mul_f32 v[124:125], v[92:93], v[124:125]
	v_pk_fma_f32 v[122:123], v[94:95], v[126:127], v[122:123]
	v_pk_fma_f32 v[124:125], v[96:97], v[128:129], v[124:125]
	v_cvt_pk_bf16_f32 v126, v186, v187
	v_cvt_pk_bf16_f32 v127, v188, v189
	v_cvt_pk_bf16_f32 v128, v122, v123
	v_cvt_pk_bf16_f32 v129, v124, v125
	s_mov_b64 s[42:43], 0x48800
	v_lshl_add_u64 v[184:185], v[246:247], 0, s[42:43]
	global_store_dwordx4 v[184:185], v[126:129], off
	s_add_i32 s6, s6, 2
	v_mov_b32_e32 v0, s6
	v_cndmask_b32_e64 v250, v155, v0, s[36:37]
	v_lshlrev_b32_e32 v250, 7, v250
	v_lshl_add_u64 v[248:249], v[166:167], 0, v[250:251]
	global_load_dwordx4 v[90:93], v[248:249], off
	v_lshl_add_u64 v[248:249], v[164:165], 0, v[250:251]
	global_load_dwordx4 v[94:97], v[248:249], off
	s_waitcnt vmcnt(9)
	v_pk_mul_f32 v[186:187], v[82:83], v[118:119]
	v_pk_mul_f32 v[188:189], v[84:85], v[120:121]
	v_pk_fma_f32 v[186:187], v[86:87], v[114:115], v[186:187] neg_lo:[0,0,1] neg_hi:[0,0,1]
	v_pk_fma_f32 v[188:189], v[88:89], v[116:117], v[188:189] neg_lo:[0,0,1] neg_hi:[0,0,1]
	v_pk_mul_f32 v[114:115], v[82:83], v[114:115]
	v_pk_mul_f32 v[116:117], v[84:85], v[116:117]
	v_pk_fma_f32 v[114:115], v[86:87], v[118:119], v[114:115]
	v_pk_fma_f32 v[116:117], v[88:89], v[120:121], v[116:117]
	v_cvt_pk_bf16_f32 v118, v186, v187
	v_cvt_pk_bf16_f32 v119, v188, v189
	v_cvt_pk_bf16_f32 v120, v114, v115
	v_cvt_pk_bf16_f32 v121, v116, v117
	global_store_dwordx4 v[184:185], v[118:121], off offset:64
	v_lshl_add_u64 v[248:249], v[168:169], 0, v[250:251]
	global_load_dwordx4 v[82:85], v[248:249], off
	v_lshl_add_u64 v[248:249], v[170:171], 0, v[250:251]
	global_load_dwordx4 v[86:89], v[248:249], off
	s_waitcnt vmcnt(9)
	v_pk_mul_f32 v[186:187], v[74:75], v[110:111]
	v_pk_mul_f32 v[188:189], v[76:77], v[112:113]
	v_pk_fma_f32 v[186:187], v[78:79], v[106:107], v[186:187] neg_lo:[0,0,1] neg_hi:[0,0,1]
	v_pk_fma_f32 v[188:189], v[80:81], v[108:109], v[188:189] neg_lo:[0,0,1] neg_hi:[0,0,1]
	v_pk_mul_f32 v[106:107], v[74:75], v[106:107]
	v_pk_mul_f32 v[108:109], v[76:77], v[108:109]
	v_pk_fma_f32 v[106:107], v[78:79], v[110:111], v[106:107]
	v_pk_fma_f32 v[108:109], v[80:81], v[112:113], v[108:109]
	v_cvt_pk_bf16_f32 v110, v186, v187
	v_cvt_pk_bf16_f32 v111, v188, v189
	v_cvt_pk_bf16_f32 v112, v106, v107
	v_cvt_pk_bf16_f32 v113, v108, v109
	s_mov_b64 s[42:43], 0x6cc00
	v_lshl_add_u64 v[184:185], v[246:247], 0, s[42:43]
	global_store_dwordx4 v[184:185], v[110:113], off
	v_mov_b32_e32 v0, s6
	v_cndmask_b32_e64 v250, v225, v0, s[36:37]
	v_lshlrev_b32_e32 v250, 7, v250
	v_lshl_add_u64 v[248:249], v[166:167], 0, v[250:251]
	global_load_dwordx4 v[74:77], v[248:249], off
	v_lshl_add_u64 v[248:249], v[164:165], 0, v[250:251]
	global_load_dwordx4 v[78:81], v[248:249], off
	s_waitcnt vmcnt(9)
	v_pk_mul_f32 v[186:187], v[66:67], v[102:103]
	v_pk_mul_f32 v[188:189], v[68:69], v[104:105]
	v_pk_fma_f32 v[186:187], v[70:71], v[98:99], v[186:187] neg_lo:[0,0,1] neg_hi:[0,0,1]
	v_pk_fma_f32 v[188:189], v[72:73], v[100:101], v[188:189] neg_lo:[0,0,1] neg_hi:[0,0,1]
	v_pk_mul_f32 v[98:99], v[66:67], v[98:99]
	v_pk_mul_f32 v[100:101], v[68:69], v[100:101]
	v_pk_fma_f32 v[98:99], v[70:71], v[102:103], v[98:99]
	v_pk_fma_f32 v[100:101], v[72:73], v[104:105], v[100:101]
	v_cvt_pk_bf16_f32 v102, v186, v187
	v_cvt_pk_bf16_f32 v103, v188, v189
	v_cvt_pk_bf16_f32 v104, v98, v99
	v_cvt_pk_bf16_f32 v105, v100, v101
	global_store_dwordx4 v[184:185], v[102:105], off offset:64
	v_lshl_add_u64 v[248:249], v[168:169], 0, v[250:251]
	global_load_dwordx4 v[66:69], v[248:249], off
	v_lshl_add_u64 v[248:249], v[170:171], 0, v[250:251]
	global_load_dwordx4 v[70:73], v[248:249], off
	s_waitcnt vmcnt(9)
	v_pk_mul_f32 v[186:187], v[58:59], v[94:95]
	v_pk_mul_f32 v[188:189], v[60:61], v[96:97]
	v_pk_fma_f32 v[186:187], v[62:63], v[90:91], v[186:187] neg_lo:[0,0,1] neg_hi:[0,0,1]
	v_pk_fma_f32 v[188:189], v[64:65], v[92:93], v[188:189] neg_lo:[0,0,1] neg_hi:[0,0,1]
	v_pk_mul_f32 v[90:91], v[58:59], v[90:91]
	v_pk_mul_f32 v[92:93], v[60:61], v[92:93]
	v_pk_fma_f32 v[90:91], v[62:63], v[94:95], v[90:91]
	v_pk_fma_f32 v[92:93], v[64:65], v[96:97], v[92:93]
	v_cvt_pk_bf16_f32 v94, v186, v187
	v_cvt_pk_bf16_f32 v95, v188, v189
	v_cvt_pk_bf16_f32 v96, v90, v91
	v_cvt_pk_bf16_f32 v97, v92, v93
	s_mov_b64 s[42:43], 0x122000
	v_lshl_add_u64 v[184:185], v[246:247], 0, s[42:43]
	global_store_dwordx4 v[184:185], v[94:97], off
	v_mov_b32_e32 v0, s6
	v_cndmask_b32_e64 v250, v226, v0, s[36:37]
	v_lshlrev_b32_e32 v250, 7, v250
	v_lshl_add_u64 v[248:249], v[166:167], 0, v[250:251]
	global_load_dwordx4 v[58:61], v[248:249], off
	v_lshl_add_u64 v[248:249], v[164:165], 0, v[250:251]
	global_load_dwordx4 v[62:65], v[248:249], off
	s_waitcnt vmcnt(9)
	v_pk_mul_f32 v[186:187], v[50:51], v[86:87]
	v_pk_mul_f32 v[188:189], v[52:53], v[88:89]
	v_pk_fma_f32 v[186:187], v[54:55], v[82:83], v[186:187] neg_lo:[0,0,1] neg_hi:[0,0,1]
	v_pk_fma_f32 v[188:189], v[56:57], v[84:85], v[188:189] neg_lo:[0,0,1] neg_hi:[0,0,1]
	v_pk_mul_f32 v[82:83], v[50:51], v[82:83]
	v_pk_mul_f32 v[84:85], v[52:53], v[84:85]
	v_pk_fma_f32 v[82:83], v[54:55], v[86:87], v[82:83]
	v_pk_fma_f32 v[84:85], v[56:57], v[88:89], v[84:85]
	v_cvt_pk_bf16_f32 v86, v186, v187
	v_cvt_pk_bf16_f32 v87, v188, v189
	v_cvt_pk_bf16_f32 v88, v82, v83
	v_cvt_pk_bf16_f32 v89, v84, v85
	global_store_dwordx4 v[184:185], v[86:89], off offset:64
	v_lshl_add_u64 v[248:249], v[168:169], 0, v[250:251]
	global_load_dwordx4 v[50:53], v[248:249], off
	v_lshl_add_u64 v[248:249], v[170:171], 0, v[250:251]
	global_load_dwordx4 v[54:57], v[248:249], off
	s_waitcnt vmcnt(9)
	v_pk_mul_f32 v[186:187], v[42:43], v[78:79]
	v_pk_mul_f32 v[188:189], v[44:45], v[80:81]
	v_pk_fma_f32 v[186:187], v[46:47], v[74:75], v[186:187] neg_lo:[0,0,1] neg_hi:[0,0,1]
	v_pk_fma_f32 v[188:189], v[48:49], v[76:77], v[188:189] neg_lo:[0,0,1] neg_hi:[0,0,1]
	v_pk_mul_f32 v[74:75], v[42:43], v[74:75]
	v_pk_mul_f32 v[76:77], v[44:45], v[76:77]
	v_pk_fma_f32 v[74:75], v[46:47], v[78:79], v[74:75]
	v_pk_fma_f32 v[76:77], v[48:49], v[80:81], v[76:77]
	v_cvt_pk_bf16_f32 v78, v186, v187
	v_cvt_pk_bf16_f32 v79, v188, v189
	v_cvt_pk_bf16_f32 v80, v74, v75
	v_cvt_pk_bf16_f32 v81, v76, v77
	s_mov_b64 s[42:43], 0x146400
	v_lshl_add_u64 v[184:185], v[246:247], 0, s[42:43]
	global_store_dwordx4 v[184:185], v[78:81], off
	v_mov_b32_e32 v0, s6
	v_cndmask_b32_e64 v250, v227, v0, s[36:37]
	v_lshlrev_b32_e32 v250, 7, v250
	v_lshl_add_u64 v[248:249], v[166:167], 0, v[250:251]
	global_load_dwordx4 v[42:45], v[248:249], off
	v_lshl_add_u64 v[248:249], v[164:165], 0, v[250:251]
	global_load_dwordx4 v[46:49], v[248:249], off
	s_waitcnt vmcnt(9)
	v_pk_mul_f32 v[186:187], v[34:35], v[70:71]
	v_pk_mul_f32 v[188:189], v[36:37], v[72:73]
	v_pk_fma_f32 v[186:187], v[38:39], v[66:67], v[186:187] neg_lo:[0,0,1] neg_hi:[0,0,1]
	v_pk_fma_f32 v[188:189], v[40:41], v[68:69], v[188:189] neg_lo:[0,0,1] neg_hi:[0,0,1]
	v_pk_mul_f32 v[66:67], v[34:35], v[66:67]
	v_pk_mul_f32 v[68:69], v[36:37], v[68:69]
	v_pk_fma_f32 v[66:67], v[38:39], v[70:71], v[66:67]
	v_pk_fma_f32 v[68:69], v[40:41], v[72:73], v[68:69]
	v_cvt_pk_bf16_f32 v70, v186, v187
	v_cvt_pk_bf16_f32 v71, v188, v189
	v_cvt_pk_bf16_f32 v72, v66, v67
	v_cvt_pk_bf16_f32 v73, v68, v69
	global_store_dwordx4 v[184:185], v[70:73], off offset:64
	v_lshl_add_u64 v[248:249], v[168:169], 0, v[250:251]
	global_load_dwordx4 v[34:37], v[248:249], off
	v_lshl_add_u64 v[248:249], v[170:171], 0, v[250:251]
	global_load_dwordx4 v[38:41], v[248:249], off
	s_waitcnt vmcnt(9)
	v_pk_mul_f32 v[186:187], v[26:27], v[62:63]
	v_pk_mul_f32 v[188:189], v[28:29], v[64:65]
	v_pk_fma_f32 v[186:187], v[30:31], v[58:59], v[186:187] neg_lo:[0,0,1] neg_hi:[0,0,1]
	v_pk_fma_f32 v[188:189], v[32:33], v[60:61], v[188:189] neg_lo:[0,0,1] neg_hi:[0,0,1]
	v_pk_mul_f32 v[58:59], v[26:27], v[58:59]
	v_pk_mul_f32 v[60:61], v[28:29], v[60:61]
	v_pk_fma_f32 v[58:59], v[30:31], v[62:63], v[58:59]
	v_pk_fma_f32 v[60:61], v[32:33], v[64:65], v[60:61]
	v_cvt_pk_bf16_f32 v62, v186, v187
	v_cvt_pk_bf16_f32 v63, v188, v189
	v_cvt_pk_bf16_f32 v64, v58, v59
	v_cvt_pk_bf16_f32 v65, v60, v61
	s_mov_b64 s[42:43], 0x16a800
	v_lshl_add_u64 v[184:185], v[246:247], 0, s[42:43]
	global_store_dwordx4 v[184:185], v[62:65], off
	s_waitcnt vmcnt(7)
	v_pk_mul_f32 v[186:187], v[18:19], v[54:55]
	v_pk_mul_f32 v[188:189], v[20:21], v[56:57]
	v_pk_fma_f32 v[186:187], v[22:23], v[50:51], v[186:187] neg_lo:[0,0,1] neg_hi:[0,0,1]
	v_pk_fma_f32 v[188:189], v[24:25], v[52:53], v[188:189] neg_lo:[0,0,1] neg_hi:[0,0,1]
	v_pk_mul_f32 v[50:51], v[18:19], v[50:51]
	v_pk_mul_f32 v[52:53], v[20:21], v[52:53]
	v_pk_fma_f32 v[50:51], v[22:23], v[54:55], v[50:51]
	v_pk_fma_f32 v[52:53], v[24:25], v[56:57], v[52:53]
	v_cvt_pk_bf16_f32 v54, v186, v187
	v_cvt_pk_bf16_f32 v55, v188, v189
	v_cvt_pk_bf16_f32 v56, v50, v51
	v_cvt_pk_bf16_f32 v57, v52, v53
	global_store_dwordx4 v[184:185], v[54:57], off offset:64
	s_waitcnt vmcnt(5)
	v_pk_mul_f32 v[186:187], v[10:11], v[46:47]
	v_pk_mul_f32 v[188:189], v[12:13], v[48:49]
	v_pk_fma_f32 v[186:187], v[14:15], v[42:43], v[186:187] neg_lo:[0,0,1] neg_hi:[0,0,1]
	v_pk_fma_f32 v[188:189], v[16:17], v[44:45], v[188:189] neg_lo:[0,0,1] neg_hi:[0,0,1]
	v_pk_mul_f32 v[42:43], v[10:11], v[42:43]
	v_pk_mul_f32 v[44:45], v[12:13], v[44:45]
	v_pk_fma_f32 v[42:43], v[14:15], v[46:47], v[42:43]
	v_pk_fma_f32 v[44:45], v[16:17], v[48:49], v[44:45]
	v_cvt_pk_bf16_f32 v46, v186, v187
	v_cvt_pk_bf16_f32 v47, v188, v189
	v_cvt_pk_bf16_f32 v48, v42, v43
	v_cvt_pk_bf16_f32 v49, v44, v45
	s_mov_b64 s[42:43], 0x18ec00
	v_lshl_add_u64 v[184:185], v[246:247], 0, s[42:43]
	global_store_dwordx4 v[184:185], v[46:49], off
	s_waitcnt vmcnt(3)
	v_pk_mul_f32 v[186:187], v[2:3], v[38:39]
	v_pk_mul_f32 v[188:189], v[4:5], v[40:41]
	v_pk_fma_f32 v[186:187], v[6:7], v[34:35], v[186:187] neg_lo:[0,0,1] neg_hi:[0,0,1]
	v_pk_fma_f32 v[188:189], v[8:9], v[36:37], v[188:189] neg_lo:[0,0,1] neg_hi:[0,0,1]
	v_pk_mul_f32 v[34:35], v[2:3], v[34:35]
	v_pk_mul_f32 v[36:37], v[4:5], v[36:37]
	v_pk_fma_f32 v[34:35], v[6:7], v[38:39], v[34:35]
	v_pk_fma_f32 v[36:37], v[8:9], v[40:41], v[36:37]
	v_cvt_pk_bf16_f32 v38, v186, v187
	v_cvt_pk_bf16_f32 v39, v188, v189
	v_cvt_pk_bf16_f32 v40, v34, v35
	v_cvt_pk_bf16_f32 v41, v36, v37
	global_store_dwordx4 v[184:185], v[38:41], off offset:64
	s_branch .LBB0_375
